# norm2 row loop software-pipelined (next row's loads issued before reducing the current row): pays now that norm phases are no longer all-CU bandwidth-saturated
# speedup vs baseline: 1.0137x; 1.0137x over previous
.LBB0_116:
	global_load_dwordx4 v[68:71], v[66:67], off offset:-3072 nt
	global_load_dwordx4 v[72:75], v[66:67], off offset:-2048 nt
	global_load_dwordx4 v[88:91], v[66:67], off offset:-1024 nt
	global_load_dwordx4 v[92:95], v[66:67], off nt
	global_load_dwordx2 v[96:97], v[64:65], off nt
	global_load_dwordx2 v[98:99], v[64:65], off offset:512 nt
	global_load_dwordx2 v[100:101], v[64:65], off offset:1024 nt
	global_load_dwordx2 v[102:103], v[64:65], off offset:1536 nt
	v_add_co_u32_e32 v122, vcc, 0xec800000, v64
	v_add_u32_e32 v86, 32, v86
	s_nop 0
	v_addc_co_u32_e32 v123, vcc, -1, v65, vcc
	v_lshl_add_u64 v[66:67], v[66:67], 0, s[6:7]
	v_lshl_add_u64 v[64:65], v[64:65], 0, s[2:3]
	v_cmp_lt_i32_e64 s[12:13], v86, v77
	s_nop 1
	s_and_b64 vcc, exec, s[12:13]
	s_cbranch_vccz .Lnrm1_nonext_first
	global_load_dwordx4 v[140:143], v[66:67], off offset:-3072 nt
	global_load_dwordx4 v[144:147], v[66:67], off offset:-2048 nt
	global_load_dwordx4 v[148:151], v[66:67], off offset:-1024 nt
	global_load_dwordx4 v[152:155], v[66:67], off nt
	global_load_dwordx2 v[156:157], v[64:65], off nt
	global_load_dwordx2 v[158:159], v[64:65], off offset:512 nt
	global_load_dwordx2 v[160:161], v[64:65], off offset:1024 nt
	global_load_dwordx2 v[162:163], v[64:65], off offset:1536 nt
	s_waitcnt vmcnt(8)
	s_branch .Lnrm1_go_first

.Lnrm1_loop:
	v_add_co_u32_e32 v122, vcc, 0xec800000, v64
	v_add_u32_e32 v86, 32, v86
	s_nop 0
	v_addc_co_u32_e32 v123, vcc, -1, v65, vcc
	v_lshl_add_u64 v[66:67], v[66:67], 0, s[6:7]
	v_lshl_add_u64 v[64:65], v[64:65], 0, s[2:3]
	v_cmp_lt_i32_e64 s[12:13], v86, v77
	s_nop 1
	s_and_b64 vcc, exec, s[12:13]
	s_cbranch_vccz .Lnrm1_nonext_a
	global_load_dwordx4 v[140:143], v[66:67], off offset:-3072 nt
	global_load_dwordx4 v[144:147], v[66:67], off offset:-2048 nt
	global_load_dwordx4 v[148:151], v[66:67], off offset:-1024 nt
	global_load_dwordx4 v[152:155], v[66:67], off nt
	global_load_dwordx2 v[156:157], v[64:65], off nt
	global_load_dwordx2 v[158:159], v[64:65], off offset:512 nt
	global_load_dwordx2 v[160:161], v[64:65], off offset:1024 nt
	global_load_dwordx2 v[162:163], v[64:65], off offset:1536 nt
	s_waitcnt vmcnt(12)
	s_branch .Lnrm1_go_a

.Lnrm1_go_a:
	v_lshlrev_b32_e32 v106, 16, v96
	v_and_b32_e32 v107, 0xffff0000, v96
	v_lshlrev_b32_e32 v108, 16, v97
	v_and_b32_e32 v109, 0xffff0000, v97
	v_pk_fma_f32 v[68:69], v[44:45], v[106:107], v[68:69]
	v_pk_fma_f32 v[70:71], v[46:47], v[108:109], v[70:71]
	v_lshlrev_b32_e32 v106, 16, v98
	v_and_b32_e32 v107, 0xffff0000, v98
	v_lshlrev_b32_e32 v108, 16, v99
	v_and_b32_e32 v109, 0xffff0000, v99
	v_pk_fma_f32 v[72:73], v[40:41], v[106:107], v[72:73]
	v_pk_fma_f32 v[74:75], v[42:43], v[108:109], v[74:75]
	v_lshlrev_b32_e32 v106, 16, v100
	v_and_b32_e32 v107, 0xffff0000, v100
	v_lshlrev_b32_e32 v108, 16, v101
	v_and_b32_e32 v109, 0xffff0000, v101
	v_pk_fma_f32 v[88:89], v[36:37], v[106:107], v[88:89]
	v_pk_fma_f32 v[90:91], v[38:39], v[108:109], v[90:91]
	v_lshlrev_b32_e32 v106, 16, v102
	v_and_b32_e32 v107, 0xffff0000, v102
	v_lshlrev_b32_e32 v108, 16, v103
	v_and_b32_e32 v109, 0xffff0000, v103
	v_pk_fma_f32 v[92:93], v[32:33], v[106:107], v[92:93]
	v_pk_fma_f32 v[94:95], v[34:35], v[108:109], v[94:95]
	v_mul_f32_e32 v111, v69, v69
	v_fma_f32 v110, v68, v68, v111
	v_mul_f32_e32 v111, v71, v71
	v_fma_f32 v111, v70, v70, v111
	v_add_f32_e32 v112, v110, v111
	v_mul_f32_e32 v111, v73, v73
	v_fma_f32 v110, v72, v72, v111
	v_mul_f32_e32 v111, v75, v75
	v_fma_f32 v111, v74, v74, v111
	v_add_f32_e32 v113, v110, v111
	v_mul_f32_e32 v111, v89, v89
	v_fma_f32 v110, v88, v88, v111
	v_mul_f32_e32 v111, v91, v91
	v_fma_f32 v111, v90, v90, v111
	v_add_f32_e32 v114, v110, v111
	v_mul_f32_e32 v110, v92, v92
	v_mul_f32_e32 v111, v93, v93
	v_add_f32_e32 v110, v110, v111
	v_mul_f32_e32 v111, v94, v94
	v_mul_f32_e32 v115, v95, v95
	v_add_f32_e32 v111, v111, v115
	v_add_f32_e32 v115, v110, v111
	v_add_f32_e32 v112, v112, v113
	v_add_f32_e32 v112, v112, v114
	v_add_f32_e32 v112, v112, v115
	ds_bpermute_b32 v124, v80, v112
	s_waitcnt lgkmcnt(0)
	v_add_f32_e32 v112, v112, v124
	ds_bpermute_b32 v124, v81, v112
	s_waitcnt lgkmcnt(0)
	v_add_f32_e32 v112, v112, v124
	ds_bpermute_b32 v124, v82, v112
	s_waitcnt lgkmcnt(0)
	v_add_f32_e32 v112, v112, v124
	ds_bpermute_b32 v124, v83, v112
	s_waitcnt lgkmcnt(0)
	v_add_f32_e32 v112, v112, v124
	ds_bpermute_b32 v124, v84, v112
	s_waitcnt lgkmcnt(0)
	v_add_f32_e32 v112, v112, v124
	ds_bpermute_b32 v124, v85, v112
	s_waitcnt lgkmcnt(0)
	v_add_f32_e32 v112, v112, v124
	v_fmamk_f32 v112, v112, 0x3a800000, v201
	v_cmp_gt_f32_e32 vcc, s16, v112
	v_mul_f32_e32 v124, 0x4b800000, v112
	s_nop 0
	v_cndmask_b32_e32 v112, v112, v124, vcc
	v_rsq_f32_e32 v116, v112
	s_nop 0
	v_mul_f32_e32 v124, 0x45800000, v116
	v_cndmask_b32_e32 v116, v116, v124, vcc
	v_pk_mul_f32 v[106:107], v[68:69], v[116:117] op_sel_hi:[1,0]
	v_pk_mul_f32 v[108:109], v[70:71], v[116:117] op_sel_hi:[1,0]
	v_pk_mul_f32 v[106:107], v[0:1], v[106:107]
	v_pk_mul_f32 v[108:109], v[2:3], v[108:109]
	v_pk_fma_f32 v[106:107], v[50:51], v[106:107], v[16:17]
	v_pk_fma_f32 v[108:109], v[48:49], v[108:109], v[18:19]
	v_cvt_pk_bf16_f32 v120, v106, v107
	v_cvt_pk_bf16_f32 v121, v108, v109
	global_store_dwordx2 v[122:123], v[120:121], off
	v_pk_mul_f32 v[106:107], v[72:73], v[116:117] op_sel_hi:[1,0]
	v_pk_mul_f32 v[108:109], v[74:75], v[116:117] op_sel_hi:[1,0]
	v_pk_mul_f32 v[106:107], v[4:5], v[106:107]
	v_pk_mul_f32 v[108:109], v[6:7], v[108:109]
	v_pk_fma_f32 v[106:107], v[54:55], v[106:107], v[20:21]
	v_pk_fma_f32 v[108:109], v[52:53], v[108:109], v[22:23]
	v_cvt_pk_bf16_f32 v118, v106, v107
	v_cvt_pk_bf16_f32 v119, v108, v109
	global_store_dwordx2 v[122:123], v[118:119], off offset:512
	v_pk_mul_f32 v[106:107], v[88:89], v[116:117] op_sel_hi:[1,0]
	v_pk_mul_f32 v[108:109], v[90:91], v[116:117] op_sel_hi:[1,0]
	v_pk_mul_f32 v[106:107], v[8:9], v[106:107]
	v_pk_mul_f32 v[108:109], v[10:11], v[108:109]
	v_pk_fma_f32 v[106:107], v[58:59], v[106:107], v[24:25]
	v_pk_fma_f32 v[108:109], v[56:57], v[108:109], v[26:27]
	v_cvt_pk_bf16_f32 v120, v106, v107
	v_cvt_pk_bf16_f32 v121, v108, v109
	global_store_dwordx2 v[122:123], v[120:121], off offset:1024
	v_pk_mul_f32 v[106:107], v[92:93], v[116:117] op_sel_hi:[1,0]
	v_pk_mul_f32 v[108:109], v[94:95], v[116:117] op_sel_hi:[1,0]
	v_pk_mul_f32 v[106:107], v[12:13], v[106:107]
	v_pk_mul_f32 v[108:109], v[14:15], v[108:109]
	v_pk_fma_f32 v[106:107], v[62:63], v[106:107], v[28:29]
	v_pk_fma_f32 v[108:109], v[60:61], v[108:109], v[30:31]
	v_cvt_pk_bf16_f32 v118, v106, v107
	v_cvt_pk_bf16_f32 v119, v108, v109
	global_store_dwordx2 v[122:123], v[118:119], off offset:1536
	s_and_b64 vcc, exec, s[12:13]
	s_cbranch_vccz .Lnrm1_done
	v_add_co_u32_e32 v122, vcc, 0xec800000, v64
	v_add_u32_e32 v86, 32, v86
	s_nop 0
	v_addc_co_u32_e32 v123, vcc, -1, v65, vcc
	v_lshl_add_u64 v[66:67], v[66:67], 0, s[6:7]
	v_lshl_add_u64 v[64:65], v[64:65], 0, s[2:3]
	v_cmp_lt_i32_e64 s[12:13], v86, v77
	s_nop 1
	s_and_b64 vcc, exec, s[12:13]
	s_cbranch_vccz .Lnrm1_nonext_b
	global_load_dwordx4 v[68:71], v[66:67], off offset:-3072 nt
	global_load_dwordx4 v[72:75], v[66:67], off offset:-2048 nt
	global_load_dwordx4 v[88:91], v[66:67], off offset:-1024 nt
	global_load_dwordx4 v[92:95], v[66:67], off nt
	global_load_dwordx2 v[96:97], v[64:65], off nt
	global_load_dwordx2 v[98:99], v[64:65], off offset:512 nt
	global_load_dwordx2 v[100:101], v[64:65], off offset:1024 nt
	global_load_dwordx2 v[102:103], v[64:65], off offset:1536 nt
	s_waitcnt vmcnt(12)
	s_branch .Lnrm1_go_b

.Lnrm1_done:
	s_or_b64 exec, exec, s[12:13]
	s_cmp_lg_u32 s100, 0
	s_cbranch_scc1 .Lnt_done_n1
	s_mov_b32 s100, 1
	s_mov_b64 s[12:13], 0
	v_add_u32_e32 v86, 0x700, v86
	v_add_u32_e32 v77, 0x800, v77
	s_mov_b32 vcc_lo, 0x380000
	s_mov_b32 vcc_hi, 0
	v_lshl_add_u64 v[64:65], v[64:65], 0, vcc
	s_mov_b32 vcc_lo, 0x700000
	v_lshl_add_u64 v[66:67], v[66:67], 0, vcc
	s_branch .LBB0_116
